# v056 + GEMM phase prologues issue K-tile 1's staging loads together with K-tile 0's (before the first wait) instead of behind the first wait and barrier
# speedup vs baseline: 1.0041x; 1.0041x over previous
; #define PG8_STAGE(bufoff, gbase, voff) do { _Pragma("unroll") for (int _i = 0; _i < 2; ++_i) \
;         __builtin_amdgcn_global_load_lds((const unsigned*)((const char*)(gbase) + (voff)[_i]), (PG8_LAS unsigned*)(lds + (bufoff) + ldsw + _i * 8192), 16, 0, AUX_A); } while (0)
; #define PG8_STAGEB(bufoff, gbase, voff) do { _Pragma("unroll") for (int _i = 0; _i < 2; ++_i) \
;         __builtin_amdgcn_global_load_lds((const unsigned*)((const char*)(gbase) + (voff)[_i]), (PG8_LAS unsigned*)(lds + (bufoff) + ldsw + _i * 8192), 16, 0, AUX_B); } while (0)
; #define PG8_WAIT_V(n) asm volatile("s_waitcnt vmcnt(" #n ")" ::: "memory")
; #define PG8_BAR __builtin_amdgcn_s_barrier()
; template <class Epi, class Sched, bool ALIGN_EPI = false, bool SP2 = false>
; __device__ __forceinline__ void gemm_phase(PG8_LAS unsigned char* lds, const Gemm g, const Sched& S, const Epi& E) {
;     ...
;     if constexpr (SP2) {
;         PG8_STAGEB(PG8_SB(0, 0), sB0, voffB); PG8_STAGEB(PG8_SB(0, 1), sB0 + hstep, voffB); PG8_STAGE(PG8_SA(0, 0), sA0, voffA); PG8_STAGE(PG8_SA(0, 1), sA0 + hstep, voffA);
;         if (wr == 1) PG8_BAR;
;         PG8_WAIT_V(2); PG8_BAR;
;         PG8_STAGEB(PG8_SB(1, 0), sB1, voffB); PG8_STAGE(PG8_SA(1, 0), sA1, voffA); PG8_STAGEB(PG8_SB(1, 1), sB1 + hstep, voffB);
;         PG8_WAIT_V(6); PG8_BAR;
.LBB0_264:
	v_readlane_b32 s2, v254, 53
	v_readlane_b32 s3, v254, 54
	v_readlane_b32 s44, v249, 50
	s_lshl_b64 s[6:7], s[2:3], 14
	v_readlane_b32 s50, v249, 56
	v_readlane_b32 s51, v249, 57
	s_add_u32 s4, s50, s6
	s_addc_u32 s5, s51, s7
	s_lshl_b32 s78, s2, 6
	s_lshl_b32 s31, s2, 4
	s_lshl_b32 s75, s2, 2
	s_add_u32 s20, s82, 0x1ec00000
	s_addc_u32 s21, s83, 0
	v_writelane_b32 v254, s4, 60
	s_add_u32 s22, s82, 0x26100000
	s_addc_u32 s23, s83, 0
	v_writelane_b32 v254, s5, 61
	s_mov_b64 s[4:5], s[82:83]
	s_add_u32 s82, s4, 0x27300000
	s_addc_u32 s83, s5, 0
	v_bfe_u32 v99, v16, 4, 2
	s_add_u32 s2, s4, 0x800000
	v_and_b32_e32 v1, 15, v16
	v_lshlrev_b32_e32 v17, 4, v99
	v_lshlrev_b32_e32 v16, 2, v16
	v_writelane_b32 v254, s4, 62
	s_addc_u32 s3, s5, 0
	s_and_b32 s18, s1, 3
	s_lshl_b32 s6, s0, 6
	v_lshl_or_b32 v17, v1, 6, v17
	s_lshl_b32 s0, s0, 13
	v_and_b32_e32 v16, 32, v16
	v_bitop3_b32 v18, v17, s0, v16 bitop3:0xde
	s_lshl_b32 s0, s18, 5
	s_add_i32 m0, s96, 0x18000
	v_lshl_add_u64 v[6:7], v[6:7], 0, s[76:77]
	v_writelane_b32 v255, s0, 0
	s_lshl_b32 s0, s18, 12
	global_load_lds_dwordx4 v[6:7], off
	v_lshl_add_u64 v[4:5], v[4:5], 0, s[76:77]
	s_add_i32 m0, s96, 0x1a000
	s_add_i32 s90, s96, 0x8000
	s_add_i32 s91, s96, 0xa000
	v_bitop3_b32 v221, v17, s0, v16 bitop3:0xde
	global_load_lds_dwordx4 v[4:5], off
	v_lshl_add_u64 v[2:3], v[2:3], 0, s[76:77]
	s_mov_b32 m0, s90
	s_add_u32 s0, s38, 0x80080
	global_load_lds_dwordx4 v[2:3], off
	v_lshl_add_u64 v[2:3], v[8:9], 0, s[76:77]
	s_mov_b32 m0, s91
	s_addc_u32 s1, s39, 0
	global_load_lds_dwordx4 v[2:3], off
	s_add_i32 m0, s96, 0x1c000
	v_lshl_add_u64 v[2:3], s[0:1], 0, v[184:185]
	global_load_lds_dwordx4 v[2:3], off
	v_lshl_add_u64 v[2:3], s[0:1], 0, v[180:181]
	s_add_i32 m0, s96, 0x1e000
	s_cmpk_lt_u32 s16, 0x100
	global_load_lds_dwordx4 v[2:3], off
	s_waitcnt vmcnt(8)
	s_barrier
	v_lshlrev_b32_e32 v2, 15, v10
	v_and_b32_e32 v2, 0xffff0000, v2
	v_lshl_add_u32 v2, v11, 12, v2
	v_and_b32_e32 v3, 1, v10
	v_lshl_or_b32 v2, v3, 6, v2
	s_cselect_b64 s[10:11], -1, 0
	s_lshl_b32 s0, s18, 6
	v_lshl_add_u32 v188, v12, 1, v2
	v_lshlrev_b32_e32 v2, 15, v14
	v_writelane_b32 v255, s0, 1
	s_or_b32 s93, s0, 0xfffffc00
	v_and_b32_e32 v2, 0xffff0000, v2
	s_lshl_b64 s[0:1], s[78:79], 2
	s_waitcnt vmcnt(6)
	v_lshl_add_u32 v2, v13, 12, v2
	v_and_b32_e32 v3, 1, v14
	v_writelane_b32 v255, s0, 2
	v_lshl_or_b32 v2, v3, 6, v2
	v_writelane_b32 v254, s5, 63
	v_writelane_b32 v255, s1, 3
	v_readlane_b32 s0, v252, 49
	v_mov_b32_e32 v189, v98
	v_lshl_add_u32 v190, v15, 1, v2
	v_mov_b32_e32 v191, v98
	s_mov_b32 s94, 0
	v_add_u32_e32 v222, 0, v18
	v_readlane_b32 s95, v253, 5
	s_mov_b32 s78, s0
	v_readlane_b32 s45, v249, 51
	v_readlane_b32 s46, v249, 52
	v_readlane_b32 s47, v249, 53
	v_readlane_b32 s48, v249, 54
	v_readlane_b32 s49, v249, 55
	v_readlane_b32 s52, v249, 58
	v_readlane_b32 s53, v249, 59
	v_readlane_b32 s54, v249, 60
	v_readlane_b32 s55, v249, 61
	v_readlane_b32 s56, v249, 62
	v_readlane_b32 s57, v249, 63
	v_readlane_b32 s58, v250, 0
	v_readlane_b32 s59, v250, 1
	s_barrier
	v_readlane_b32 s1, v252, 50
	s_branch .LBB0_267

; #define PG8_STAGE(bufoff, gbase, voff) do { _Pragma("unroll") for (int _i = 0; _i < 2; ++_i) \
;         __builtin_amdgcn_global_load_lds((const unsigned*)((const char*)(gbase) + (voff)[_i]), (PG8_LAS unsigned*)(lds + (bufoff) + ldsw + _i * 8192), 16, 0, AUX_A); } while (0)
; #define PG8_STAGEB(bufoff, gbase, voff) do { _Pragma("unroll") for (int _i = 0; _i < 2; ++_i) \
;         __builtin_amdgcn_global_load_lds((const unsigned*)((const char*)(gbase) + (voff)[_i]), (PG8_LAS unsigned*)(lds + (bufoff) + ldsw + _i * 8192), 16, 0, AUX_B); } while (0)
; #define PG8_WAIT_V(n) asm volatile("s_waitcnt vmcnt(" #n ")" ::: "memory")
; #define PG8_BAR __builtin_amdgcn_s_barrier()
; template <class Epi, class Sched, bool ALIGN_EPI = false, bool SP2 = false>
; __device__ __forceinline__ void gemm_phase(PG8_LAS unsigned char* lds, const Gemm g, const Sched& S, const Epi& E) {
;     ...
;     if constexpr (SP2) {
;         PG8_STAGEB(PG8_SB(0, 0), sB0, voffB); PG8_STAGEB(PG8_SB(0, 1), sB0 + hstep, voffB); PG8_STAGE(PG8_SA(0, 0), sA0, voffA); PG8_STAGE(PG8_SA(0, 1), sA0 + hstep, voffA);
;         if (wr == 1) PG8_BAR;
;         PG8_WAIT_V(2); PG8_BAR;
;         PG8_STAGEB(PG8_SB(1, 0), sB1, voffB); PG8_STAGE(PG8_SA(1, 0), sA1, voffA); PG8_STAGEB(PG8_SB(1, 1), sB1 + hstep, voffB);
;         PG8_WAIT_V(6); PG8_BAR;
.LBB0_921:
	v_readlane_b32 s44, v249, 34
	s_lshl_b64 s[8:9], s[2:3], 12
	v_readlane_b32 s56, v249, 46
	v_readlane_b32 s57, v249, 47
	s_add_u32 s8, s56, s8
	v_lshrrev_b32_e32 v18, 1, v13
	s_addc_u32 s9, s57, s9
	v_and_b32_e32 v18, 24, v18
	s_add_u32 s10, s34, 0x28980000
	v_and_b32_e32 v17, 15, v13
	v_lshlrev_b32_e32 v19, 1, v18
	v_lshlrev_b32_e32 v13, 2, v13
	s_addc_u32 s11, s35, 0
	v_lshl_or_b32 v1, s0, 6, v17
	v_lshl_or_b32 v17, v17, 6, v19
	s_lshl_b32 s0, s0, 13
	v_and_b32_e32 v13, 32, v13
	v_bitop3_b32 v19, v17, s0, v13 bitop3:0xde
	s_lshl_b32 s0, s1, 5
	s_and_b32 s2, s0, 0x60
	s_add_i32 m0, s25, 0x18000
	v_lshl_add_u64 v[8:9], v[8:9], 0, s[76:77]
	s_lshl_b32 s0, s2, 7
	global_load_lds_dwordx4 v[8:9], off
	v_lshl_add_u64 v[6:7], v[6:7], 0, s[76:77]
	s_add_i32 m0, s25, 0x1a000
	s_add_i32 s70, s25, 0x8000
	s_add_i32 s71, s25, 0xa000
	v_bitop3_b32 v99, v17, s0, v13 bitop3:0xde
	global_load_lds_dwordx4 v[6:7], off
	v_lshl_add_u64 v[2:3], v[2:3], 0, s[76:77]
	s_mov_b32 m0, s70
	s_add_u32 s0, s26, 0x40080
	global_load_lds_dwordx4 v[2:3], off
	v_lshl_add_u64 v[2:3], v[4:5], 0, s[76:77]
	s_mov_b32 m0, s71
	s_addc_u32 s1, s27, 0
	global_load_lds_dwordx4 v[2:3], off
	s_add_i32 m0, s25, 0x1c000
	v_lshl_add_u64 v[2:3], s[0:1], 0, v[150:151]
	global_load_lds_dwordx4 v[2:3], off
	v_lshl_add_u64 v[2:3], s[0:1], 0, v[154:155]
	s_add_i32 m0, s25, 0x1e000
	v_readlane_b32 s45, v249, 35
	global_load_lds_dwordx4 v[2:3], off
	s_waitcnt vmcnt(8)
	s_barrier
	v_lshlrev_b32_e32 v2, 14, v14
	v_and_b32_e32 v2, 0xffff8000, v2
	v_lshl_add_u32 v2, v15, 11, v2
	v_and_b32_e32 v3, 1, v14
	v_lshl_or_b32 v2, v3, 6, v2
	v_lshl_add_u32 v156, v16, 1, v2
	v_lshlrev_b32_e32 v2, 14, v10
	v_and_b32_e32 v2, 0xffff8000, v2
	s_waitcnt vmcnt(6)
	v_lshl_add_u32 v2, v11, 11, v2
	v_and_b32_e32 v3, 1, v10
	v_readlane_b32 s48, v249, 38
	v_readlane_b32 s49, v249, 39
	v_readlane_b32 s50, v249, 40
	v_readlane_b32 s51, v249, 41
	s_cmpk_lt_u32 s12, 0x100
	v_lshl_or_b32 v2, v3, 6, v2
	s_cselect_b64 s[12:13], -1, 0
	v_or_b32_e32 v164, s2, v18
	v_mov_b32_e32 v157, v98
	v_lshl_add_u32 v158, v12, 1, v2
	v_mov_b32_e32 v159, v98
	s_mov_b32 s75, 0
	v_add_u32_e32 v165, 0, v19
	v_readlane_b32 s3, v252, 31
	v_readlane_b32 s44, v252, 33
	v_readlane_b32 s45, v252, 11
	v_readlane_b32 s48, v252, 12
	s_mov_b32 s49, 0x40000
	s_mov_b32 s50, 0x48000
	s_mov_b32 s51, 0x50000
	s_mov_b32 s66, 0x58000
	v_readlane_b32 s46, v249, 36
	v_readlane_b32 s47, v249, 37
	v_readlane_b32 s52, v249, 42
	v_readlane_b32 s53, v249, 43
	v_readlane_b32 s54, v249, 44
	v_readlane_b32 s55, v249, 45
	v_readlane_b32 s58, v249, 48
	v_readlane_b32 s59, v249, 49
	s_barrier
	s_branch .LBB0_924

; #define PG8_STAGE(bufoff, gbase, voff) do { _Pragma("unroll") for (int _i = 0; _i < 2; ++_i) \
;         __builtin_amdgcn_global_load_lds((const unsigned*)((const char*)(gbase) + (voff)[_i]), (PG8_LAS unsigned*)(lds + (bufoff) + ldsw + _i * 8192), 16, 0, AUX_A); } while (0)
; #define PG8_STAGEB(bufoff, gbase, voff) do { _Pragma("unroll") for (int _i = 0; _i < 2; ++_i) \
;         __builtin_amdgcn_global_load_lds((const unsigned*)((const char*)(gbase) + (voff)[_i]), (PG8_LAS unsigned*)(lds + (bufoff) + ldsw + _i * 8192), 16, 0, AUX_B); } while (0)
; #define PG8_WAIT_V(n) asm volatile("s_waitcnt vmcnt(" #n ")" ::: "memory")
; #define PG8_BAR __builtin_amdgcn_s_barrier()
; template <class Epi, class Sched, bool ALIGN_EPI = false, bool SP2 = false>
; __device__ __forceinline__ void gemm_phase(PG8_LAS unsigned char* lds, const Gemm g, const Sched& S, const Epi& E) {
;     ...
;     if constexpr (SP2) {
;         PG8_STAGEB(PG8_SB(0, 0), sB0, voffB); PG8_STAGEB(PG8_SB(0, 1), sB0 + hstep, voffB); PG8_STAGE(PG8_SA(0, 0), sA0, voffA); PG8_STAGE(PG8_SA(0, 1), sA0 + hstep, voffA);
;         if (wr == 1) PG8_BAR;
;         PG8_WAIT_V(2); PG8_BAR;
;         PG8_STAGEB(PG8_SB(1, 0), sB1, voffB); PG8_STAGE(PG8_SA(1, 0), sA1, voffA); PG8_STAGEB(PG8_SB(1, 1), sB1 + hstep, voffB);
;         PG8_WAIT_V(6); PG8_BAR;
.LBB0_1056:
	v_bfe_u32 v18, v16, 4, 2
	s_lshl_b32 s0, s0, 5
	v_and_b32_e32 v17, 15, v16
	v_lshlrev_b32_e32 v19, 4, v18
	v_lshlrev_b32_e32 v16, 2, v16
	s_and_b32 s2, s0, 0x60
	s_add_i32 m0, s71, 0x18000
	v_lshl_add_u64 v[8:9], v[8:9], 0, s[76:77]
	v_lshl_or_b32 v1, s1, 6, v17
	v_lshl_or_b32 v19, v17, 6, v19
	s_lshl_b32 s1, s1, 13
	v_and_b32_e32 v16, 32, v16
	s_lshl_b32 s0, s2, 7
	global_load_lds_dwordx4 v[8:9], off
	v_lshl_add_u64 v[6:7], v[6:7], 0, s[76:77]
	s_add_i32 m0, s71, 0x1a000
	s_add_i32 s83, s71, 0x8000
	s_add_i32 s88, s71, 0xa000
	v_bitop3_b32 v99, v19, s0, v16 bitop3:0xde
	global_load_lds_dwordx4 v[6:7], off
	v_lshl_add_u64 v[2:3], v[2:3], 0, s[76:77]
	s_mov_b32 m0, s83
	s_add_u32 s0, s42, 0x40080
	v_bitop3_b32 v20, v19, s1, v16 bitop3:0xde
	global_load_lds_dwordx4 v[2:3], off
	v_lshl_add_u64 v[2:3], v[4:5], 0, s[76:77]
	s_mov_b32 m0, s88
	s_addc_u32 s1, s43, 0
	global_load_lds_dwordx4 v[2:3], off
	s_add_i32 m0, s71, 0x1c000
	v_lshl_add_u64 v[2:3], s[0:1], 0, v[136:137]
	global_load_lds_dwordx4 v[2:3], off
	v_lshl_add_u64 v[2:3], s[0:1], 0, v[132:133]
	s_add_i32 m0, s71, 0x1e000
	v_lshl_or_b32 v150, v18, 3, s2
	global_load_lds_dwordx4 v[2:3], off
	s_waitcnt vmcnt(8)
	s_barrier
	v_or_b32_e32 v2, v18, v17
	v_cmp_eq_u32_e64 s[40:41], 0, v2
	v_lshlrev_b32_e32 v2, 14, v10
	v_and_b32_e32 v2, 0xffff8000, v2
	v_lshl_add_u32 v2, v11, 11, v2
	v_and_b32_e32 v3, 1, v10
	v_lshl_or_b32 v2, v3, 6, v2
	v_lshl_add_u32 v140, v12, 1, v2
	v_lshlrev_b32_e32 v2, 14, v14
	v_and_b32_e32 v2, 0xffff8000, v2
	v_readlane_b32 s2, v253, 1
	s_waitcnt vmcnt(6)
	v_lshl_add_u32 v2, v13, 11, v2
	v_and_b32_e32 v3, 1, v14
	v_readlane_b32 s3, v253, 2
	s_cmpk_lt_u32 s12, 0x100
	v_lshl_or_b32 v2, v3, 6, v2
	s_mov_b32 s91, s2
	v_readlane_b32 s2, v252, 61
	s_cselect_b64 s[12:13], -1, 0
	s_mov_b32 s0, 0
	v_mov_b32_e32 v141, v98
	v_lshl_add_u32 v142, v15, 1, v2
	v_mov_b32_e32 v143, v98
	v_add_u32_e32 v151, 0, v20
	s_mov_b32 s90, s2
	s_barrier
	v_readlane_b32 s3, v252, 62
	s_branch .LBB0_1059

; #define PG8_STAGE(bufoff, gbase, voff) do { _Pragma("unroll") for (int _i = 0; _i < 2; ++_i) \
;         __builtin_amdgcn_global_load_lds((const unsigned*)((const char*)(gbase) + (voff)[_i]), (PG8_LAS unsigned*)(lds + (bufoff) + ldsw + _i * 8192), 16, 0, AUX_A); } while (0)
; #define PG8_STAGEB(bufoff, gbase, voff) do { _Pragma("unroll") for (int _i = 0; _i < 2; ++_i) \
;         __builtin_amdgcn_global_load_lds((const unsigned*)((const char*)(gbase) + (voff)[_i]), (PG8_LAS unsigned*)(lds + (bufoff) + ldsw + _i * 8192), 16, 0, AUX_B); } while (0)
; #define PG8_WAIT_V(n) asm volatile("s_waitcnt vmcnt(" #n ")" ::: "memory")
; #define PG8_BAR __builtin_amdgcn_s_barrier()
; template <class Epi, class Sched, bool ALIGN_EPI = false, bool SP2 = false>
; __device__ __forceinline__ void gemm_phase(PG8_LAS unsigned char* lds, const Gemm g, const Sched& S, const Epi& E) {
;     ...
;     if constexpr (SP2) {
;         PG8_STAGEB(PG8_SB(0, 0), sB0, voffB); PG8_STAGEB(PG8_SB(0, 1), sB0 + hstep, voffB); PG8_STAGE(PG8_SA(0, 0), sA0, voffA); PG8_STAGE(PG8_SA(0, 1), sA0 + hstep, voffA);
;         if (wr == 1) PG8_BAR;
;         PG8_WAIT_V(2); PG8_BAR;
;         PG8_STAGEB(PG8_SB(1, 0), sB1, voffB); PG8_STAGE(PG8_SA(1, 0), sA1, voffA); PG8_STAGEB(PG8_SB(1, 1), sB1 + hstep, voffB);
;         PG8_WAIT_V(6); PG8_BAR;
.LBB0_1146:
	s_add_u32 s14, s4, 0x2d180000
	v_lshrrev_b32_e32 v18, 1, v16
	s_addc_u32 s15, s5, 0
	v_and_b32_e32 v18, 24, v18
	s_lshl_b32 s0, s0, 5
	v_and_b32_e32 v17, 15, v16
	v_lshlrev_b32_e32 v19, 1, v18
	v_lshlrev_b32_e32 v16, 2, v16
	s_and_b32 s2, s0, 0x60
	s_add_i32 m0, s71, 0x18000
	v_lshl_add_u64 v[8:9], v[8:9], 0, s[76:77]
	v_lshl_or_b32 v1, s1, 6, v17
	v_lshl_or_b32 v17, v17, 6, v19
	s_lshl_b32 s1, s1, 13
	v_and_b32_e32 v16, 32, v16
	s_lshl_b32 s0, s2, 7
	global_load_lds_dwordx4 v[8:9], off
	v_lshl_add_u64 v[6:7], v[6:7], 0, s[76:77]
	s_add_i32 m0, s71, 0x1a000
	s_add_i32 s83, s71, 0x8000
	s_add_i32 s88, s71, 0xa000
	v_bitop3_b32 v99, v17, s0, v16 bitop3:0xde
	global_load_lds_dwordx4 v[6:7], off
	v_lshl_add_u64 v[2:3], v[2:3], 0, s[76:77]
	s_mov_b32 m0, s83
	s_add_u32 s0, s50, 0x40080
	v_bitop3_b32 v19, v17, s1, v16 bitop3:0xde
	global_load_lds_dwordx4 v[2:3], off
	v_lshl_add_u64 v[2:3], v[4:5], 0, s[76:77]
	s_mov_b32 m0, s88
	s_addc_u32 s1, s51, 0
	global_load_lds_dwordx4 v[2:3], off
	s_add_i32 m0, s71, 0x1c000
	v_lshl_add_u64 v[2:3], s[0:1], 0, v[136:137]
	global_load_lds_dwordx4 v[2:3], off
	v_lshl_add_u64 v[2:3], s[0:1], 0, v[132:133]
	s_add_i32 m0, s71, 0x1e000
	v_or_b32_e32 v152, s2, v18
	global_load_lds_dwordx4 v[2:3], off
	s_waitcnt vmcnt(8)
	s_barrier
	v_lshlrev_b32_e32 v2, 14, v10
	v_and_b32_e32 v2, 0xffff8000, v2
	v_lshl_add_u32 v2, v11, 11, v2
	v_and_b32_e32 v3, 1, v10
	v_lshl_or_b32 v2, v3, 6, v2
	v_lshl_add_u32 v140, v12, 1, v2
	v_lshlrev_b32_e32 v2, 14, v14
	v_and_b32_e32 v2, 0xffff8000, v2
	v_readlane_b32 s2, v253, 1
	s_waitcnt vmcnt(6)
	v_lshl_add_u32 v2, v13, 11, v2
	v_and_b32_e32 v3, 1, v14
	v_readlane_b32 s3, v253, 2
	s_cmpk_lt_u32 s16, 0x100
	v_lshl_or_b32 v2, v3, 6, v2
	s_mov_b32 s91, s2
	v_readlane_b32 s2, v252, 61
	s_cselect_b64 s[16:17], -1, 0
	v_mov_b32_e32 v141, v98
	v_lshl_add_u32 v142, v15, 1, v2
	v_mov_b32_e32 v143, v98
	s_mov_b32 s0, 0
	v_add_u32_e32 v153, 0, v19
	s_mov_b32 s90, s2
	s_barrier
	v_readlane_b32 s3, v252, 62
	s_branch .LBB0_1149

; #define PG8_STAGE(bufoff, gbase, voff) do { _Pragma("unroll") for (int _i = 0; _i < 2; ++_i) \
;         __builtin_amdgcn_global_load_lds((const unsigned*)((const char*)(gbase) + (voff)[_i]), (PG8_LAS unsigned*)(lds + (bufoff) + ldsw + _i * 8192), 16, 0, AUX_A); } while (0)
; #define PG8_STAGEB(bufoff, gbase, voff) do { _Pragma("unroll") for (int _i = 0; _i < 2; ++_i) \
;         __builtin_amdgcn_global_load_lds((const unsigned*)((const char*)(gbase) + (voff)[_i]), (PG8_LAS unsigned*)(lds + (bufoff) + ldsw + _i * 8192), 16, 0, AUX_B); } while (0)
; #define PG8_WAIT_V(n) asm volatile("s_waitcnt vmcnt(" #n ")" ::: "memory")
; #define PG8_BAR __builtin_amdgcn_s_barrier()
; template <class Epi, class Sched, bool ALIGN_EPI = false, bool SP2 = false>
; __device__ __forceinline__ void gemm_phase(PG8_LAS unsigned char* lds, const Gemm g, const Sched& S, const Epi& E) {
;     ...
;     if constexpr (SP2) {
;         PG8_STAGEB(PG8_SB(0, 0), sB0, voffB); PG8_STAGEB(PG8_SB(0, 1), sB0 + hstep, voffB); PG8_STAGE(PG8_SA(0, 0), sA0, voffA); PG8_STAGE(PG8_SA(0, 1), sA0 + hstep, voffA);
;         if (wr == 1) PG8_BAR;
;         PG8_WAIT_V(2); PG8_BAR;
;         PG8_STAGEB(PG8_SB(1, 0), sB1, voffB); PG8_STAGE(PG8_SA(1, 0), sA1, voffA); PG8_STAGEB(PG8_SB(1, 1), sB1 + hstep, voffB);
;         PG8_WAIT_V(6); PG8_BAR;
.LBB0_1294:
	s_add_u32 s6, s8, 0x39880000
	s_mul_i32 s11, s64, 0xf0000
	s_addc_u32 s7, s9, 0
	s_mul_hi_u32 s2, s64, 0xf0000
	s_add_u32 s11, s8, s11
	s_addc_u32 s2, s9, s2
	s_add_u32 s54, s11, 0x104000
	s_addc_u32 s55, s2, 0
	s_add_u32 s56, s8, 0x35880000
	v_lshrrev_b32_e32 v17, 1, v16
	s_addc_u32 s57, s9, 0
	v_and_b32_e32 v17, 24, v17
	s_lshl_b32 s0, s0, 5
	v_and_b32_e32 v1, 15, v16
	v_lshlrev_b32_e32 v18, 1, v17
	v_lshlrev_b32_e32 v16, 2, v16
	s_and_b32 s2, s0, 0x60
	s_add_i32 m0, s50, 0x18000
	v_lshl_add_u64 v[8:9], v[8:9], 0, s[76:77]
	s_lshl_b32 s58, s1, 6
	v_lshl_or_b32 v18, v1, 6, v18
	s_lshl_b32 s1, s1, 13
	v_and_b32_e32 v16, 32, v16
	s_lshl_b32 s0, s2, 7
	global_load_lds_dwordx4 v[8:9], off
	v_lshl_add_u64 v[6:7], v[6:7], 0, s[76:77]
	s_add_i32 m0, s50, 0x1a000
	s_add_i32 s59, s50, 0x8000
	s_add_i32 s60, s50, 0xa000
	v_bitop3_b32 v99, v18, s0, v16 bitop3:0xde
	global_load_lds_dwordx4 v[6:7], off
	v_lshl_add_u64 v[2:3], v[2:3], 0, s[76:77]
	s_mov_b32 m0, s59
	s_add_u32 s0, s34, 0x80080
	v_bitop3_b32 v19, v18, s1, v16 bitop3:0xde
	global_load_lds_dwordx4 v[2:3], off
	v_lshl_add_u64 v[2:3], v[4:5], 0, s[76:77]
	s_mov_b32 m0, s60
	s_addc_u32 s1, s35, 0
	global_load_lds_dwordx4 v[2:3], off
	s_add_i32 m0, s50, 0x1c000
	v_lshl_add_u64 v[2:3], s[0:1], 0, v[156:157]
	global_load_lds_dwordx4 v[2:3], off
	v_lshl_add_u64 v[2:3], s[0:1], 0, v[152:153]
	s_add_i32 m0, s50, 0x1e000
	s_cmpk_lt_u32 s10, 0x100
	global_load_lds_dwordx4 v[2:3], off
	s_waitcnt vmcnt(8)
	s_barrier
	v_lshlrev_b32_e32 v2, 15, v10
	v_and_b32_e32 v2, 0xffff0000, v2
	v_lshl_add_u32 v2, v11, 12, v2
	v_and_b32_e32 v3, 1, v10
	v_lshl_or_b32 v2, v3, 6, v2
	v_lshl_add_u32 v160, v12, 1, v2
	v_lshlrev_b32_e32 v2, 15, v14
	v_and_b32_e32 v2, 0xffff0000, v2
	s_waitcnt vmcnt(6)
	v_lshl_add_u32 v2, v13, 12, v2
	v_and_b32_e32 v3, 1, v14
	v_lshl_or_b32 v2, v3, 6, v2
	v_readlane_b32 s0, v252, 45
	s_cselect_b64 s[8:9], -1, 0
	v_or_b32_e32 v180, s2, v17
	v_mov_b32_e32 v161, v98
	v_lshl_add_u32 v162, v15, 1, v2
	v_mov_b32_e32 v163, v98
	s_mov_b32 s61, 0
	v_add_u32_e32 v181, 0, v19
	s_mov_b32 s78, s0
	v_readlane_b32 s71, v252, 46
	v_readlane_b32 s70, v252, 59
	v_readlane_b32 s69, v252, 57
	s_mov_b32 s3, 0x20000
	s_mov_b32 s46, 0x30000
	s_barrier
	s_branch .LBB0_1297

; #define PG8_STAGE(bufoff, gbase, voff) do { _Pragma("unroll") for (int _i = 0; _i < 2; ++_i) \
;         __builtin_amdgcn_global_load_lds((const unsigned*)((const char*)(gbase) + (voff)[_i]), (PG8_LAS unsigned*)(lds + (bufoff) + ldsw + _i * 8192), 16, 0, AUX_A); } while (0)
; #define PG8_STAGEB(bufoff, gbase, voff) do { _Pragma("unroll") for (int _i = 0; _i < 2; ++_i) \
;         __builtin_amdgcn_global_load_lds((const unsigned*)((const char*)(gbase) + (voff)[_i]), (PG8_LAS unsigned*)(lds + (bufoff) + ldsw + _i * 8192), 16, 0, AUX_B); } while (0)
; #define PG8_WAIT_V(n) asm volatile("s_waitcnt vmcnt(" #n ")" ::: "memory")
; #define PG8_BAR __builtin_amdgcn_s_barrier()
; template <class Epi, class Sched, bool ALIGN_EPI = false, bool SP2 = false>
; __device__ __forceinline__ void gemm_phase(PG8_LAS unsigned char* lds, const Gemm g, const Sched& S, const Epi& E) {
;     ...
;     if constexpr (SP2) {
;         PG8_STAGEB(PG8_SB(0, 0), sB0, voffB); PG8_STAGEB(PG8_SB(0, 1), sB0 + hstep, voffB); PG8_STAGE(PG8_SA(0, 0), sA0, voffA); PG8_STAGE(PG8_SA(0, 1), sA0 + hstep, voffA);
;         if (wr == 1) PG8_BAR;
;         PG8_WAIT_V(2); PG8_BAR;
;         PG8_STAGEB(PG8_SB(1, 0), sB1, voffB); PG8_STAGE(PG8_SA(1, 0), sA1, voffA); PG8_STAGEB(PG8_SB(1, 1), sB1 + hstep, voffB);
;         PG8_WAIT_V(6); PG8_BAR;
.LBB0_1452:
	s_add_u32 s8, s4, 0x2f580000
	v_lshrrev_b32_e32 v18, 1, v16
	s_addc_u32 s9, s5, 0
	v_and_b32_e32 v18, 24, v18
	s_lshl_b32 s0, s0, 5
	v_and_b32_e32 v17, 15, v16
	v_lshlrev_b32_e32 v19, 1, v18
	v_lshlrev_b32_e32 v16, 2, v16
	s_and_b32 s2, s0, 0x60
	s_add_i32 m0, s57, 0x18000
	v_lshl_add_u64 v[8:9], v[8:9], 0, s[76:77]
	v_lshl_or_b32 v1, s1, 6, v17
	v_lshl_or_b32 v17, v17, 6, v19
	s_lshl_b32 s1, s1, 13
	v_and_b32_e32 v16, 32, v16
	s_lshl_b32 s0, s2, 7
	global_load_lds_dwordx4 v[8:9], off
	v_lshl_add_u64 v[6:7], v[6:7], 0, s[76:77]
	s_add_i32 m0, s57, 0x1a000
	s_add_i32 s61, s57, 0x8000
	s_add_i32 s62, s57, 0xa000
	v_bitop3_b32 v99, v17, s0, v16 bitop3:0xde
	global_load_lds_dwordx4 v[6:7], off
	s_add_u32 s0, s34, 0x80080
	v_bitop3_b32 v19, v17, s1, v16 bitop3:0xde
	s_addc_u32 s1, s35, 0
	s_add_i32 m0, s57, 0x1c000
	v_lshl_add_u64 v[2:3], s[0:1], 0, v[136:137]
	global_load_lds_dwordx4 v[2:3], off
	v_lshl_add_u64 v[2:3], s[0:1], 0, v[132:133]
	s_add_i32 m0, s57, 0x1e000
	s_cmpk_lt_u32 s10, 0x100
	global_load_lds_dwordx4 v[2:3], off
	s_waitcnt vmcnt(6)
	s_barrier
	v_lshlrev_b32_e32 v2, 15, v10
	v_and_b32_e32 v2, 0xffff0000, v2
	v_lshl_add_u32 v2, v11, 12, v2
	v_and_b32_e32 v3, 1, v10
	v_lshl_or_b32 v2, v3, 6, v2
	v_lshl_add_u32 v140, v12, 1, v2
	v_lshlrev_b32_e32 v2, 15, v14
	v_and_b32_e32 v2, 0xffff0000, v2
	s_waitcnt vmcnt(4)
	v_lshl_add_u32 v2, v13, 12, v2
	v_and_b32_e32 v3, 1, v14
	v_lshl_or_b32 v2, v3, 6, v2
	v_readlane_b32 s0, v252, 37
	s_cselect_b64 s[10:11], -1, 0
	v_or_b32_e32 v148, s2, v18
	v_mov_b32_e32 v141, v98
	v_lshl_add_u32 v142, v15, 1, v2
	v_mov_b32_e32 v143, v98
	s_mov_b32 s63, 0
	v_add_u32_e32 v149, 0, v19
	v_readlane_b32 s69, v253, 6
	s_mov_b32 s70, s0
	s_movk_i32 s3, 0xc7
	s_mov_b32 s64, 0x58000
	s_mov_b32 s65, 0x2c000
	s_mov_b32 s66, 0x84000
	s_barrier
	v_readlane_b32 s1, v252, 38
	s_branch .LBB0_1455

; #define PG8_STAGE(bufoff, gbase, voff) do { _Pragma("unroll") for (int _i = 0; _i < 2; ++_i) \
;         __builtin_amdgcn_global_load_lds((const unsigned*)((const char*)(gbase) + (voff)[_i]), (PG8_LAS unsigned*)(lds + (bufoff) + ldsw + _i * 8192), 16, 0, AUX_A); } while (0)
; #define PG8_STAGEB(bufoff, gbase, voff) do { _Pragma("unroll") for (int _i = 0; _i < 2; ++_i) \
;         __builtin_amdgcn_global_load_lds((const unsigned*)((const char*)(gbase) + (voff)[_i]), (PG8_LAS unsigned*)(lds + (bufoff) + ldsw + _i * 8192), 16, 0, AUX_B); } while (0)
; #define PG8_WAIT_V(n) asm volatile("s_waitcnt vmcnt(" #n ")" ::: "memory")
; #define PG8_BAR __builtin_amdgcn_s_barrier()
; template <class Epi, class Sched, bool ALIGN_EPI = false, bool SP2 = false>
; __device__ __forceinline__ void gemm_phase(PG8_LAS unsigned char* lds, const Gemm g, const Sched& S, const Epi& E) {
;     ...
;     if constexpr (SP2) {
;         PG8_STAGEB(PG8_SB(0, 0), sB0, voffB); PG8_STAGEB(PG8_SB(0, 1), sB0 + hstep, voffB); PG8_STAGE(PG8_SA(0, 0), sA0, voffA); PG8_STAGE(PG8_SA(0, 1), sA0 + hstep, voffA);
;         if (wr == 1) PG8_BAR;
;         PG8_WAIT_V(2); PG8_BAR;
;         PG8_STAGEB(PG8_SB(1, 0), sB1, voffB); PG8_STAGE(PG8_SA(1, 0), sA1, voffA); PG8_STAGEB(PG8_SB(1, 1), sB1 + hstep, voffB);
;         PG8_WAIT_V(6); PG8_BAR;
.LBB0_1641:
	s_cmp_eq_u32 s8, 3
	s_cselect_b32 s7, s65, 0
	s_cselect_b32 s6, s64, 0
	s_cmp_lg_u64 s[6:7], 0
	s_cselect_b64 s[8:9], -1, 0
	s_add_u32 s10, s12, 0x39880000
	s_addc_u32 s11, s13, 0
	v_readlane_b32 s2, v254, 57
	s_add_u32 s2, s12, s2
	v_readlane_b32 s3, v254, 56
	s_addc_u32 s15, s13, s3
	s_add_u32 s55, s2, 0x10a000
	s_addc_u32 s56, s15, 0
	s_add_u32 s57, s12, 0x35880000
	v_lshrrev_b32_e32 v19, 1, v18
	s_addc_u32 s58, s13, 0
	v_and_b32_e32 v19, 24, v19
	s_lshl_b32 s0, s0, 5
	v_and_b32_e32 v1, 15, v18
	v_lshlrev_b32_e32 v20, 1, v19
	v_lshlrev_b32_e32 v18, 2, v18
	s_and_b32 s2, s0, 0x60
	s_add_i32 m0, s50, 0x18000
	v_lshl_add_u64 v[8:9], v[8:9], 0, s[76:77]
	s_lshl_b32 s59, s1, 6
	v_lshl_or_b32 v20, v1, 6, v20
	s_lshl_b32 s1, s1, 13
	v_and_b32_e32 v18, 32, v18
	s_lshl_b32 s0, s2, 7
	global_load_lds_dwordx4 v[8:9], off
	v_lshl_add_u64 v[6:7], v[6:7], 0, s[76:77]
	s_add_i32 m0, s50, 0x1a000
	s_add_i32 s60, s50, 0x8000
	s_add_i32 s61, s50, 0xa000
	v_bitop3_b32 v99, v20, s0, v18 bitop3:0xde
	global_load_lds_dwordx4 v[6:7], off
	v_lshl_add_u64 v[2:3], v[2:3], 0, s[76:77]
	s_mov_b32 m0, s60
	s_add_u32 s0, s34, 0x160080
	v_bitop3_b32 v21, v20, s1, v18 bitop3:0xde
	global_load_lds_dwordx4 v[2:3], off
	v_lshl_add_u64 v[2:3], v[4:5], 0, s[76:77]
	s_mov_b32 m0, s61
	s_addc_u32 s1, s35, 0
	global_load_lds_dwordx4 v[2:3], off
	s_add_i32 m0, s50, 0x1c000
	v_lshl_add_u64 v[2:3], s[0:1], 0, v[160:161]
	global_load_lds_dwordx4 v[2:3], off
	v_lshl_add_u64 v[2:3], s[0:1], 0, v[156:157]
	s_add_i32 m0, s50, 0x1e000
	v_or_b32_e32 v188, s2, v19
	global_load_lds_dwordx4 v[2:3], off
	s_waitcnt vmcnt(8)
	s_barrier
	s_movk_i32 s2, 0x1600
	v_lshrrev_b32_e32 v3, 1, v10
	v_mul_lo_u32 v2, v11, s2
	s_mov_b32 s3, 0x16000
	v_mad_u64_u32 v[2:3], s[0:1], v3, s3, v[2:3]
	v_or_b32_e32 v2, v2, v12
	v_add_lshl_u32 v164, v2, v13, 1
	v_lshrrev_b32_e32 v3, 1, v15
	v_mul_lo_u32 v2, v14, s2
	s_waitcnt vmcnt(6)
	v_mad_u64_u32 v[2:3], s[0:1], v3, s3, v[2:3]
	s_cmpk_lt_u32 s14, 0x100
	v_or_b32_e32 v2, v2, v16
	v_readlane_b32 s0, v252, 45
	s_mov_b32 s54, 0
	s_cselect_b64 s[12:13], -1, 0
	v_mov_b32_e32 v165, v98
	v_add_lshl_u32 v166, v2, v17, 1
	v_mov_b32_e32 v167, v98
	v_add_u32_e32 v189, 0, v21
	s_mov_b32 s78, s0
	v_readlane_b32 s82, v252, 42
	v_readlane_b32 s75, v252, 59
	v_readlane_b32 s71, v252, 57
	s_mov_b32 s3, 0x20000
	s_mov_b32 s47, 0x30000
	s_mov_b64 s[64:65], 0x40000
	s_mov_b64 s[66:67], 0x10000
	s_barrier
	s_branch .LBB0_1644
